# in-proj GEMM epilogue stores tagged nt (streaming outputs no longer evict the A/B tiles from L2)
# speedup vs baseline: 1.0313x; 1.0249x over previous
; __device__ __forceinline__ unsigned pk2(float lo, float hi) { f32x2_t v = {lo, hi}; bf16x2_t b = __builtin_convertvector(v, bf16x2_t); return __builtin_bit_cast(unsigned, b); }
; __device__ __forceinline__ float silu_f(float v) { return v * __builtin_amdgcn_rcpf(1.f + __builtin_amdgcn_exp2f(-v * LOG2E)); }
; template <int CTRL> __device__ __forceinline__ unsigned dpp_mov(unsigned v) { return (unsigned)__builtin_amdgcn_update_dpp(0, (int)v, CTRL, 0xF, 0xF, true); }
;     __device__ __forceinline__ void operator()(const pg8::f32x4 (&acc)[2][2][4][2], const pg8::Unit& u, int wr, int wc, int fr, int fq) const {
;     ...
;                 pg8::f32x4 a0 = acc[ai][0][m][0], a1 = acc[ai][0][m][1], b0 = acc[ai][1][m][0], b1 = acc[ai][1][m][1];
;                 if (act) {
; #pragma unroll
;                     for (int e = 0; e < 4; ++e) { a0[e] = silu_f(a0[e]); a1[e] = silu_f(a1[e]); b0[e] = silu_f(b0[e]); b1[e] = silu_f(b1[e]); } }
;                 u32x4 A, B; A.x = pk2(a0[0], a0[1]); A.y = pk2(a0[2], a0[3]); A.z = pk2(a1[0], a1[1]); A.w = pk2(a1[2], a1[3]);
;                 B.x = pk2(b0[0], b0[1]); B.y = pk2(b0[2], b0[3]); B.z = pk2(b1[0], b1[1]); B.w = pk2(b1[2], b1[3]);
;                 u32x4 snd, rcv;
; #pragma unroll
;                 for (int e = 0; e < 4; ++e) { snd[e] = hi8 ? A[e] : B[e]; rcv[e] = dpp_mov<0x128>(snd[e]); }
;                 u32x4 d1, d2;
; #pragma unroll
;                 for (int e = 0; e < 4; ++e) { d1[e] = hi8 ? rcv[e] : A[e]; d2[e] = hi8 ? B[e] : rcv[e]; }
;                 const int row1 = rbase + ai * 128 + m * 16, row2 = row1 + 8;
;                 if (qkv) {
;                     const int bb = row1 >> 13, t1 = row1 & (SEQ - 1), t2 = row2 & (SEQ - 1);
;                     const int p1 = (t1 & dmask) * Lc + (t1 >> dsh), p2 = (t2 & dmask) * Lc + (t2 >> dsh);
;                     bf16_t* hb = base + (size_t)bb * 24 * SEQ * 64 + ecol;
;                     *(u32x4*)(hb + (size_t)p1 * 64) = d1; *(u32x4*)(hb + (size_t)p2 * 64) = d2;
.Lp1_nn0:
	s_lshl_b32 s6, s6, 8
	s_add_i32 s62, s6, s74
	s_lshl_b64 s[6:7], s[8:9], 1
	s_add_u32 s6, s60, s6
	s_addc_u32 s7, s61, s7
	s_sub_i32 s21, 13, s17
	v_lshl_add_u64 v[140:141], s[6:7], 0, v[132:133]
	s_and_b64 s[6:7], s[58:59], exec
	s_cselect_b32 s8, 9, 10
	s_ashr_i32 s6, s62, 13
	v_cvt_pk_bf16_f32 v124, v124, v125
	v_cvt_pk_bf16_f32 v125, v126, v127
	v_cvt_pk_bf16_f32 v120, v120, v121
	v_cvt_pk_bf16_f32 v121, v122, v123
	v_cvt_pk_bf16_f32 v117, v116, v117
	v_cvt_pk_bf16_f32 v118, v118, v119
	v_cvt_pk_bf16_f32 v119, v112, v113
	v_cvt_pk_bf16_f32 v115, v114, v115
	s_mul_i32 s6, s6, 24
	v_cndmask_b32_e64 v112, v124, v117, s[0:1]
	v_cndmask_b32_e64 v113, v125, v118, s[0:1]
	v_cndmask_b32_e64 v114, v120, v119, s[0:1]
	v_cndmask_b32_e64 v116, v121, v115, s[0:1]
	s_ashr_i32 s7, s6, 31
	v_mov_b32_dpp v112, v112 row_ror:8 row_mask:0xf bank_mask:0xf bound_ctrl:1
	v_mov_b32_dpp v113, v113 row_ror:8 row_mask:0xf bank_mask:0xf bound_ctrl:1
	v_mov_b32_dpp v114, v114 row_ror:8 row_mask:0xf bank_mask:0xf bound_ctrl:1
	v_mov_b32_dpp v122, v116 row_ror:8 row_mask:0xf bank_mask:0xf bound_ctrl:1
	s_lshl_b64 s[6:7], s[6:7], 20
	v_or_b32_e32 v142, s62, v147
	v_cndmask_b32_e64 v116, v112, v124, s[0:1]
	v_cndmask_b32_e64 v112, v117, v112, s[0:1]
	v_cndmask_b32_e64 v117, v113, v125, s[0:1]
	v_cndmask_b32_e64 v113, v118, v113, s[0:1]
	v_cndmask_b32_e64 v118, v114, v120, s[0:1]
	v_cndmask_b32_e64 v114, v119, v114, s[0:1]
	v_cndmask_b32_e64 v119, v122, v121, s[0:1]
	v_cndmask_b32_e64 v121, 0, 1, s[28:29]
	v_lshl_add_u64 v[144:145], v[140:141], 0, s[6:7]
	v_cndmask_b32_e64 v115, v115, v122, s[0:1]
	v_or_b32_e32 v120, 8, v142
	v_cmp_ne_u32_e64 s[6:7], 1, v121
	s_andn2_b64 vcc, exec, s[28:29]
	s_mov_b64 s[28:29], -1
	s_cbranch_vccnz .LBB0_206
	v_and_b32_e32 v121, 0x1fc7, v142
	v_lshlrev_b32_e32 v123, s21, v142
	v_and_b32_e32 v122, 0x1fcf, v120
	v_and_b32_e32 v123, 0x1ffe, v123
	v_lshrrev_b32_e32 v121, s17, v121
	v_lshlrev_b32_e32 v124, s21, v120
	v_lshrrev_b32_e32 v125, s17, v122
	v_add_lshl_u32 v122, v123, v121, 7
	v_mov_b32_e32 v123, v133
	v_and_b32_e32 v124, 0x1ffe, v124
	v_lshl_add_u64 v[122:123], v[144:145], 0, v[122:123]
	global_store_dwordx4 v[122:123], v[116:119], off nt
	v_add_lshl_u32 v122, v124, v125, 7
	v_mov_b32_e32 v123, v133
	v_lshl_add_u64 v[122:123], v[144:145], 0, v[122:123]
	global_store_dwordx4 v[122:123], v[112:115], off nt
	s_cbranch_execz .LBB0_207

; __device__ __forceinline__ unsigned pk2(float lo, float hi) { f32x2_t v = {lo, hi}; bf16x2_t b = __builtin_convertvector(v, bf16x2_t); return __builtin_bit_cast(unsigned, b); }
; __device__ __forceinline__ float silu_f(float v) { return v * __builtin_amdgcn_rcpf(1.f + __builtin_amdgcn_exp2f(-v * LOG2E)); }
; template <int CTRL> __device__ __forceinline__ unsigned dpp_mov(unsigned v) { return (unsigned)__builtin_amdgcn_update_dpp(0, (int)v, CTRL, 0xF, 0xF, true); }
;     __device__ __forceinline__ void operator()(const pg8::f32x4 (&acc)[2][2][4][2], const pg8::Unit& u, int wr, int wc, int fr, int fq) const {
;     ...
;                 pg8::f32x4 a0 = acc[ai][0][m][0], a1 = acc[ai][0][m][1], b0 = acc[ai][1][m][0], b1 = acc[ai][1][m][1];
;                 if (act) {
; #pragma unroll
;                     for (int e = 0; e < 4; ++e) { a0[e] = silu_f(a0[e]); a1[e] = silu_f(a1[e]); b0[e] = silu_f(b0[e]); b1[e] = silu_f(b1[e]); } }
;                 u32x4 A, B; A.x = pk2(a0[0], a0[1]); A.y = pk2(a0[2], a0[3]); A.z = pk2(a1[0], a1[1]); A.w = pk2(a1[2], a1[3]);
;                 B.x = pk2(b0[0], b0[1]); B.y = pk2(b0[2], b0[3]); B.z = pk2(b1[0], b1[1]); B.w = pk2(b1[2], b1[3]);
;                 u32x4 snd, rcv;
; #pragma unroll
;                 for (int e = 0; e < 4; ++e) { snd[e] = hi8 ? A[e] : B[e]; rcv[e] = dpp_mov<0x128>(snd[e]); }
;                 u32x4 d1, d2;
; #pragma unroll
;                 for (int e = 0; e < 4; ++e) { d1[e] = hi8 ? rcv[e] : A[e]; d2[e] = hi8 ? B[e] : rcv[e]; }
;                 const int row1 = rbase + ai * 128 + m * 16, row2 = row1 + 8;
;                 if (qkv) {
;                     const int bb = row1 >> 13, t1 = row1 & (SEQ - 1), t2 = row2 & (SEQ - 1);
;                     const int p1 = (t1 & dmask) * Lc + (t1 >> dsh), p2 = (t2 & dmask) * Lc + (t2 >> dsh);
;                     bf16_t* hb = base + (size_t)bb * 24 * SEQ * 64 + ecol;
;                     *(u32x4*)(hb + (size_t)p1 * 64) = d1; *(u32x4*)(hb + (size_t)p2 * 64) = d2;
.Lp1_nn1:
	v_cvt_pk_bf16_f32 v108, v108, v109
	v_cvt_pk_bf16_f32 v109, v110, v111
	v_cvt_pk_bf16_f32 v104, v104, v105
	v_cvt_pk_bf16_f32 v105, v106, v107
	v_cvt_pk_bf16_f32 v101, v100, v101
	v_cvt_pk_bf16_f32 v102, v102, v103
	v_cvt_pk_bf16_f32 v103, v96, v97
	v_cvt_pk_bf16_f32 v99, v98, v99
	v_cndmask_b32_e64 v96, v108, v101, s[0:1]
	v_cndmask_b32_e64 v97, v109, v102, s[0:1]
	v_cndmask_b32_e64 v98, v104, v103, s[0:1]
	v_cndmask_b32_e64 v100, v105, v99, s[0:1]
	v_mov_b32_dpp v96, v96 row_ror:8 row_mask:0xf bank_mask:0xf bound_ctrl:1
	v_mov_b32_dpp v97, v97 row_ror:8 row_mask:0xf bank_mask:0xf bound_ctrl:1
	v_mov_b32_dpp v98, v98 row_ror:8 row_mask:0xf bank_mask:0xf bound_ctrl:1
	v_mov_b32_dpp v106, v100 row_ror:8 row_mask:0xf bank_mask:0xf bound_ctrl:1
	v_cndmask_b32_e64 v100, v96, v108, s[0:1]
	v_cndmask_b32_e64 v96, v101, v96, s[0:1]
	v_cndmask_b32_e64 v101, v97, v109, s[0:1]
	v_cndmask_b32_e64 v97, v102, v97, s[0:1]
	v_cndmask_b32_e64 v102, v98, v104, s[0:1]
	v_cndmask_b32_e64 v98, v103, v98, s[0:1]
	v_cndmask_b32_e64 v103, v106, v105, s[0:1]
	v_cndmask_b32_e64 v99, v99, v106, s[0:1]
	v_or_b32_e32 v106, 16, v142
	v_or_b32_e32 v104, 24, v142
	s_and_b64 vcc, exec, s[6:7]
	s_mov_b64 s[28:29], -1
	s_cbranch_vccnz .LBB0_208
	v_and_b32_e32 v105, 0x1fd7, v106
	v_lshlrev_b32_e32 v108, s21, v105
	v_and_b32_e32 v108, 0x1ffe, v108
	v_lshrrev_b32_e32 v105, s17, v105
	v_lshlrev_b32_e32 v109, s21, v104
	v_and_b32_e32 v107, 0x1fdf, v104
	v_and_b32_e32 v110, 0x1ffe, v109
	v_add_lshl_u32 v108, v108, v105, 7
	v_mov_b32_e32 v109, v133
	v_lshrrev_b32_e32 v107, s17, v107
	v_lshl_add_u64 v[108:109], v[144:145], 0, v[108:109]
	global_store_dwordx4 v[108:109], v[100:103], off nt
	v_add_lshl_u32 v108, v110, v107, 7
	v_mov_b32_e32 v109, v133
	v_lshl_add_u64 v[108:109], v[144:145], 0, v[108:109]
	global_store_dwordx4 v[108:109], v[96:99], off nt
	s_cbranch_execz .LBB0_209

; __device__ __forceinline__ unsigned pk2(float lo, float hi) { f32x2_t v = {lo, hi}; bf16x2_t b = __builtin_convertvector(v, bf16x2_t); return __builtin_bit_cast(unsigned, b); }
; __device__ __forceinline__ float silu_f(float v) { return v * __builtin_amdgcn_rcpf(1.f + __builtin_amdgcn_exp2f(-v * LOG2E)); }
; template <int CTRL> __device__ __forceinline__ unsigned dpp_mov(unsigned v) { return (unsigned)__builtin_amdgcn_update_dpp(0, (int)v, CTRL, 0xF, 0xF, true); }
;     __device__ __forceinline__ void operator()(const pg8::f32x4 (&acc)[2][2][4][2], const pg8::Unit& u, int wr, int wc, int fr, int fq) const {
;     ...
;                 pg8::f32x4 a0 = acc[ai][0][m][0], a1 = acc[ai][0][m][1], b0 = acc[ai][1][m][0], b1 = acc[ai][1][m][1];
;                 if (act) {
; #pragma unroll
;                     for (int e = 0; e < 4; ++e) { a0[e] = silu_f(a0[e]); a1[e] = silu_f(a1[e]); b0[e] = silu_f(b0[e]); b1[e] = silu_f(b1[e]); } }
;                 u32x4 A, B; A.x = pk2(a0[0], a0[1]); A.y = pk2(a0[2], a0[3]); A.z = pk2(a1[0], a1[1]); A.w = pk2(a1[2], a1[3]);
;                 B.x = pk2(b0[0], b0[1]); B.y = pk2(b0[2], b0[3]); B.z = pk2(b1[0], b1[1]); B.w = pk2(b1[2], b1[3]);
;                 u32x4 snd, rcv;
; #pragma unroll
;                 for (int e = 0; e < 4; ++e) { snd[e] = hi8 ? A[e] : B[e]; rcv[e] = dpp_mov<0x128>(snd[e]); }
;                 u32x4 d1, d2;
; #pragma unroll
;                 for (int e = 0; e < 4; ++e) { d1[e] = hi8 ? rcv[e] : A[e]; d2[e] = hi8 ? B[e] : rcv[e]; }
;                 const int row1 = rbase + ai * 128 + m * 16, row2 = row1 + 8;
;                 if (qkv) {
;                     const int bb = row1 >> 13, t1 = row1 & (SEQ - 1), t2 = row2 & (SEQ - 1);
;                     const int p1 = (t1 & dmask) * Lc + (t1 >> dsh), p2 = (t2 & dmask) * Lc + (t2 >> dsh);
;                     bf16_t* hb = base + (size_t)bb * 24 * SEQ * 64 + ecol;
;                     *(u32x4*)(hb + (size_t)p1 * 64) = d1; *(u32x4*)(hb + (size_t)p2 * 64) = d2;
.Lp1_nn2:
	v_cvt_pk_bf16_f32 v92, v92, v93
	v_cvt_pk_bf16_f32 v93, v94, v95
	v_cvt_pk_bf16_f32 v88, v88, v89
	v_cvt_pk_bf16_f32 v89, v90, v91
	v_cvt_pk_bf16_f32 v85, v84, v85
	v_cvt_pk_bf16_f32 v86, v86, v87
	v_cvt_pk_bf16_f32 v87, v80, v81
	v_cvt_pk_bf16_f32 v83, v82, v83
	v_cndmask_b32_e64 v80, v92, v85, s[0:1]
	v_cndmask_b32_e64 v81, v93, v86, s[0:1]
	v_cndmask_b32_e64 v82, v88, v87, s[0:1]
	v_cndmask_b32_e64 v84, v89, v83, s[0:1]
	v_mov_b32_dpp v80, v80 row_ror:8 row_mask:0xf bank_mask:0xf bound_ctrl:1
	v_mov_b32_dpp v81, v81 row_ror:8 row_mask:0xf bank_mask:0xf bound_ctrl:1
	v_mov_b32_dpp v82, v82 row_ror:8 row_mask:0xf bank_mask:0xf bound_ctrl:1
	v_mov_b32_dpp v90, v84 row_ror:8 row_mask:0xf bank_mask:0xf bound_ctrl:1
	v_cndmask_b32_e64 v84, v80, v92, s[0:1]
	v_cndmask_b32_e64 v80, v85, v80, s[0:1]
	v_cndmask_b32_e64 v85, v81, v93, s[0:1]
	v_cndmask_b32_e64 v81, v86, v81, s[0:1]
	v_cndmask_b32_e64 v86, v82, v88, s[0:1]
	v_cndmask_b32_e64 v82, v87, v82, s[0:1]
	v_cndmask_b32_e64 v87, v90, v89, s[0:1]
	v_cndmask_b32_e64 v83, v83, v90, s[0:1]
	v_or_b32_e32 v90, 32, v142
	v_or_b32_e32 v88, 40, v142
	s_and_b64 vcc, exec, s[6:7]
	s_mov_b64 s[28:29], -1
	s_cbranch_vccnz .LBB0_210
	v_and_b32_e32 v89, 0x1fe7, v90
	v_lshlrev_b32_e32 v92, s21, v89
	v_and_b32_e32 v92, 0x1ffe, v92
	v_lshrrev_b32_e32 v89, s17, v89
	v_lshlrev_b32_e32 v93, s21, v88
	v_and_b32_e32 v91, 0x1fef, v88
	v_and_b32_e32 v94, 0x1ffe, v93
	v_add_lshl_u32 v92, v92, v89, 7
	v_mov_b32_e32 v93, v133
	v_lshrrev_b32_e32 v91, s17, v91
	v_lshl_add_u64 v[92:93], v[144:145], 0, v[92:93]
	global_store_dwordx4 v[92:93], v[84:87], off nt
	v_add_lshl_u32 v92, v94, v91, 7
	v_mov_b32_e32 v93, v133
	v_lshl_add_u64 v[92:93], v[144:145], 0, v[92:93]
	global_store_dwordx4 v[92:93], v[80:83], off nt
	s_cbranch_execz .LBB0_211

; __device__ __forceinline__ unsigned pk2(float lo, float hi) { f32x2_t v = {lo, hi}; bf16x2_t b = __builtin_convertvector(v, bf16x2_t); return __builtin_bit_cast(unsigned, b); }
; __device__ __forceinline__ float silu_f(float v) { return v * __builtin_amdgcn_rcpf(1.f + __builtin_amdgcn_exp2f(-v * LOG2E)); }
; template <int CTRL> __device__ __forceinline__ unsigned dpp_mov(unsigned v) { return (unsigned)__builtin_amdgcn_update_dpp(0, (int)v, CTRL, 0xF, 0xF, true); }
;     __device__ __forceinline__ void operator()(const pg8::f32x4 (&acc)[2][2][4][2], const pg8::Unit& u, int wr, int wc, int fr, int fq) const {
;     ...
;                 pg8::f32x4 a0 = acc[ai][0][m][0], a1 = acc[ai][0][m][1], b0 = acc[ai][1][m][0], b1 = acc[ai][1][m][1];
;                 if (act) {
; #pragma unroll
;                     for (int e = 0; e < 4; ++e) { a0[e] = silu_f(a0[e]); a1[e] = silu_f(a1[e]); b0[e] = silu_f(b0[e]); b1[e] = silu_f(b1[e]); } }
;                 u32x4 A, B; A.x = pk2(a0[0], a0[1]); A.y = pk2(a0[2], a0[3]); A.z = pk2(a1[0], a1[1]); A.w = pk2(a1[2], a1[3]);
;                 B.x = pk2(b0[0], b0[1]); B.y = pk2(b0[2], b0[3]); B.z = pk2(b1[0], b1[1]); B.w = pk2(b1[2], b1[3]);
;                 u32x4 snd, rcv;
; #pragma unroll
;                 for (int e = 0; e < 4; ++e) { snd[e] = hi8 ? A[e] : B[e]; rcv[e] = dpp_mov<0x128>(snd[e]); }
;                 u32x4 d1, d2;
; #pragma unroll
;                 for (int e = 0; e < 4; ++e) { d1[e] = hi8 ? rcv[e] : A[e]; d2[e] = hi8 ? B[e] : rcv[e]; }
;                 const int row1 = rbase + ai * 128 + m * 16, row2 = row1 + 8;
;                 if (qkv) {
;                     const int bb = row1 >> 13, t1 = row1 & (SEQ - 1), t2 = row2 & (SEQ - 1);
;                     const int p1 = (t1 & dmask) * Lc + (t1 >> dsh), p2 = (t2 & dmask) * Lc + (t2 >> dsh);
;                     bf16_t* hb = base + (size_t)bb * 24 * SEQ * 64 + ecol;
;                     *(u32x4*)(hb + (size_t)p1 * 64) = d1; *(u32x4*)(hb + (size_t)p2 * 64) = d2;
.Lp1_nn3:
	v_cvt_pk_bf16_f32 v76, v76, v77
	v_cvt_pk_bf16_f32 v77, v78, v79
	v_cvt_pk_bf16_f32 v72, v72, v73
	v_cvt_pk_bf16_f32 v73, v74, v75
	v_cvt_pk_bf16_f32 v69, v68, v69
	v_cvt_pk_bf16_f32 v70, v70, v71
	v_cvt_pk_bf16_f32 v71, v64, v65
	v_cvt_pk_bf16_f32 v67, v66, v67
	v_cndmask_b32_e64 v64, v76, v69, s[0:1]
	v_cndmask_b32_e64 v65, v77, v70, s[0:1]
	v_cndmask_b32_e64 v66, v72, v71, s[0:1]
	v_cndmask_b32_e64 v68, v73, v67, s[0:1]
	v_mov_b32_dpp v64, v64 row_ror:8 row_mask:0xf bank_mask:0xf bound_ctrl:1
	v_mov_b32_dpp v65, v65 row_ror:8 row_mask:0xf bank_mask:0xf bound_ctrl:1
	v_mov_b32_dpp v66, v66 row_ror:8 row_mask:0xf bank_mask:0xf bound_ctrl:1
	v_mov_b32_dpp v74, v68 row_ror:8 row_mask:0xf bank_mask:0xf bound_ctrl:1
	v_cndmask_b32_e64 v68, v64, v76, s[0:1]
	v_cndmask_b32_e64 v64, v69, v64, s[0:1]
	v_cndmask_b32_e64 v69, v65, v77, s[0:1]
	v_cndmask_b32_e64 v65, v70, v65, s[0:1]
	v_cndmask_b32_e64 v70, v66, v72, s[0:1]
	v_cndmask_b32_e64 v66, v71, v66, s[0:1]
	v_cndmask_b32_e64 v71, v74, v73, s[0:1]
	v_cndmask_b32_e64 v67, v67, v74, s[0:1]
	v_or_b32_e32 v74, 48, v142
	v_or_b32_e32 v72, 56, v142
	s_and_b64 vcc, exec, s[6:7]
	s_mov_b64 s[28:29], -1
	s_cbranch_vccnz .LBB0_212
	v_and_b32_e32 v73, 0x1ff7, v74
	v_lshlrev_b32_e32 v76, s21, v73
	v_and_b32_e32 v76, 0x1ffe, v76
	v_lshrrev_b32_e32 v73, s17, v73
	v_lshlrev_b32_e32 v77, s21, v72
	v_and_b32_e32 v75, 0x1fff, v72
	v_and_b32_e32 v78, 0x1ffe, v77
	v_add_lshl_u32 v76, v76, v73, 7
	v_mov_b32_e32 v77, v133
	v_lshrrev_b32_e32 v75, s17, v75
	v_lshl_add_u64 v[76:77], v[144:145], 0, v[76:77]
	global_store_dwordx4 v[76:77], v[68:71], off nt
	v_add_lshl_u32 v76, v78, v75, 7
	v_mov_b32_e32 v77, v133
	v_lshl_add_u64 v[76:77], v[144:145], 0, v[76:77]
	global_store_dwordx4 v[76:77], v[64:67], off nt
	s_cbranch_execz .LBB0_213

; __device__ __forceinline__ unsigned pk2(float lo, float hi) { f32x2_t v = {lo, hi}; bf16x2_t b = __builtin_convertvector(v, bf16x2_t); return __builtin_bit_cast(unsigned, b); }
; __device__ __forceinline__ float silu_f(float v) { return v * __builtin_amdgcn_rcpf(1.f + __builtin_amdgcn_exp2f(-v * LOG2E)); }
; template <int CTRL> __device__ __forceinline__ unsigned dpp_mov(unsigned v) { return (unsigned)__builtin_amdgcn_update_dpp(0, (int)v, CTRL, 0xF, 0xF, true); }
;     __device__ __forceinline__ void operator()(const pg8::f32x4 (&acc)[2][2][4][2], const pg8::Unit& u, int wr, int wc, int fr, int fq) const {
;     ...
;                 pg8::f32x4 a0 = acc[ai][0][m][0], a1 = acc[ai][0][m][1], b0 = acc[ai][1][m][0], b1 = acc[ai][1][m][1];
;                 if (act) {
; #pragma unroll
;                     for (int e = 0; e < 4; ++e) { a0[e] = silu_f(a0[e]); a1[e] = silu_f(a1[e]); b0[e] = silu_f(b0[e]); b1[e] = silu_f(b1[e]); } }
;                 u32x4 A, B; A.x = pk2(a0[0], a0[1]); A.y = pk2(a0[2], a0[3]); A.z = pk2(a1[0], a1[1]); A.w = pk2(a1[2], a1[3]);
;                 B.x = pk2(b0[0], b0[1]); B.y = pk2(b0[2], b0[3]); B.z = pk2(b1[0], b1[1]); B.w = pk2(b1[2], b1[3]);
;                 u32x4 snd, rcv;
; #pragma unroll
;                 for (int e = 0; e < 4; ++e) { snd[e] = hi8 ? A[e] : B[e]; rcv[e] = dpp_mov<0x128>(snd[e]); }
;                 u32x4 d1, d2;
; #pragma unroll
;                 for (int e = 0; e < 4; ++e) { d1[e] = hi8 ? rcv[e] : A[e]; d2[e] = hi8 ? B[e] : rcv[e]; }
;                 const int row1 = rbase + ai * 128 + m * 16, row2 = row1 + 8;
;                 if (qkv) {
;                     const int bb = row1 >> 13, t1 = row1 & (SEQ - 1), t2 = row2 & (SEQ - 1);
;                     const int p1 = (t1 & dmask) * Lc + (t1 >> dsh), p2 = (t2 & dmask) * Lc + (t2 >> dsh);
;                     bf16_t* hb = base + (size_t)bb * 24 * SEQ * 64 + ecol;
;                     *(u32x4*)(hb + (size_t)p1 * 64) = d1; *(u32x4*)(hb + (size_t)p2 * 64) = d2;
.Lp1_nn4:
	v_add_u32_e32 v66, 0x80, v142
	v_ashrrev_i32_e32 v64, 13, v66
	v_mul_i32_i24_e32 v64, 24, v64
	v_cvt_pk_bf16_f32 v60, v60, v61
	v_cvt_pk_bf16_f32 v61, v62, v63
	v_cvt_pk_bf16_f32 v56, v56, v57
	v_cvt_pk_bf16_f32 v57, v58, v59
	v_cvt_pk_bf16_f32 v53, v52, v53
	v_cvt_pk_bf16_f32 v54, v54, v55
	v_cvt_pk_bf16_f32 v55, v48, v49
	v_cvt_pk_bf16_f32 v51, v50, v51
	v_ashrrev_i32_e32 v65, 31, v64
	v_cndmask_b32_e64 v48, v60, v53, s[0:1]
	v_cndmask_b32_e64 v49, v61, v54, s[0:1]
	v_cndmask_b32_e64 v50, v56, v55, s[0:1]
	v_cndmask_b32_e64 v52, v57, v51, s[0:1]
	v_lshlrev_b64 v[64:65], 20, v[64:65]
	v_mov_b32_dpp v48, v48 row_ror:8 row_mask:0xf bank_mask:0xf bound_ctrl:1
	v_mov_b32_dpp v49, v49 row_ror:8 row_mask:0xf bank_mask:0xf bound_ctrl:1
	v_mov_b32_dpp v50, v50 row_ror:8 row_mask:0xf bank_mask:0xf bound_ctrl:1
	v_mov_b32_dpp v58, v52 row_ror:8 row_mask:0xf bank_mask:0xf bound_ctrl:1
	v_lshl_add_u64 v[64:65], v[140:141], 0, v[64:65]
	v_cndmask_b32_e64 v52, v48, v60, s[0:1]
	v_cndmask_b32_e64 v48, v53, v48, s[0:1]
	v_cndmask_b32_e64 v53, v49, v61, s[0:1]
	v_cndmask_b32_e64 v49, v54, v49, s[0:1]
	v_cndmask_b32_e64 v54, v50, v56, s[0:1]
	v_cndmask_b32_e64 v50, v55, v50, s[0:1]
	v_cndmask_b32_e64 v55, v58, v57, s[0:1]
	v_cndmask_b32_e64 v51, v51, v58, s[0:1]
	v_add_u32_e32 v56, 0x88, v142
	s_and_b64 vcc, exec, s[6:7]
	s_mov_b64 s[28:29], -1
	s_cbranch_vccnz .LBB0_214
	v_and_b32_e32 v57, 0x1fc7, v66
	v_lshlrev_b32_e32 v59, s21, v57
	v_and_b32_e32 v58, 0x1fcf, v56
	v_and_b32_e32 v59, 0x1ffe, v59
	v_lshrrev_b32_e32 v57, s17, v57
	v_lshlrev_b32_e32 v60, s21, v56
	v_lshrrev_b32_e32 v61, s17, v58
	v_add_lshl_u32 v58, v59, v57, 7
	v_mov_b32_e32 v59, v133
	v_and_b32_e32 v60, 0x1ffe, v60
	v_lshl_add_u64 v[58:59], v[64:65], 0, v[58:59]
	global_store_dwordx4 v[58:59], v[52:55], off nt
	v_add_lshl_u32 v58, v60, v61, 7
	v_mov_b32_e32 v59, v133
	v_lshl_add_u64 v[58:59], v[64:65], 0, v[58:59]
	global_store_dwordx4 v[58:59], v[48:51], off nt
	s_cbranch_execz .LBB0_215

; __device__ __forceinline__ unsigned pk2(float lo, float hi) { f32x2_t v = {lo, hi}; bf16x2_t b = __builtin_convertvector(v, bf16x2_t); return __builtin_bit_cast(unsigned, b); }
; __device__ __forceinline__ float silu_f(float v) { return v * __builtin_amdgcn_rcpf(1.f + __builtin_amdgcn_exp2f(-v * LOG2E)); }
; template <int CTRL> __device__ __forceinline__ unsigned dpp_mov(unsigned v) { return (unsigned)__builtin_amdgcn_update_dpp(0, (int)v, CTRL, 0xF, 0xF, true); }
;     __device__ __forceinline__ void operator()(const pg8::f32x4 (&acc)[2][2][4][2], const pg8::Unit& u, int wr, int wc, int fr, int fq) const {
;     ...
;                 pg8::f32x4 a0 = acc[ai][0][m][0], a1 = acc[ai][0][m][1], b0 = acc[ai][1][m][0], b1 = acc[ai][1][m][1];
;                 if (act) {
; #pragma unroll
;                     for (int e = 0; e < 4; ++e) { a0[e] = silu_f(a0[e]); a1[e] = silu_f(a1[e]); b0[e] = silu_f(b0[e]); b1[e] = silu_f(b1[e]); } }
;                 u32x4 A, B; A.x = pk2(a0[0], a0[1]); A.y = pk2(a0[2], a0[3]); A.z = pk2(a1[0], a1[1]); A.w = pk2(a1[2], a1[3]);
;                 B.x = pk2(b0[0], b0[1]); B.y = pk2(b0[2], b0[3]); B.z = pk2(b1[0], b1[1]); B.w = pk2(b1[2], b1[3]);
;                 u32x4 snd, rcv;
; #pragma unroll
;                 for (int e = 0; e < 4; ++e) { snd[e] = hi8 ? A[e] : B[e]; rcv[e] = dpp_mov<0x128>(snd[e]); }
;                 u32x4 d1, d2;
; #pragma unroll
;                 for (int e = 0; e < 4; ++e) { d1[e] = hi8 ? rcv[e] : A[e]; d2[e] = hi8 ? B[e] : rcv[e]; }
;                 const int row1 = rbase + ai * 128 + m * 16, row2 = row1 + 8;
;                 if (qkv) {
;                     const int bb = row1 >> 13, t1 = row1 & (SEQ - 1), t2 = row2 & (SEQ - 1);
;                     const int p1 = (t1 & dmask) * Lc + (t1 >> dsh), p2 = (t2 & dmask) * Lc + (t2 >> dsh);
;                     bf16_t* hb = base + (size_t)bb * 24 * SEQ * 64 + ecol;
;                     *(u32x4*)(hb + (size_t)p1 * 64) = d1; *(u32x4*)(hb + (size_t)p2 * 64) = d2;
.Lp1_nn5:
	v_cvt_pk_bf16_f32 v44, v44, v45
	v_cvt_pk_bf16_f32 v45, v46, v47
	v_cvt_pk_bf16_f32 v40, v40, v41
	v_cvt_pk_bf16_f32 v41, v42, v43
	v_cvt_pk_bf16_f32 v37, v36, v37
	v_cvt_pk_bf16_f32 v38, v38, v39
	v_cvt_pk_bf16_f32 v39, v32, v33
	v_cvt_pk_bf16_f32 v35, v34, v35
	v_cndmask_b32_e64 v32, v44, v37, s[0:1]
	v_cndmask_b32_e64 v33, v45, v38, s[0:1]
	v_cndmask_b32_e64 v34, v40, v39, s[0:1]
	v_cndmask_b32_e64 v36, v41, v35, s[0:1]
	v_mov_b32_dpp v32, v32 row_ror:8 row_mask:0xf bank_mask:0xf bound_ctrl:1
	v_mov_b32_dpp v33, v33 row_ror:8 row_mask:0xf bank_mask:0xf bound_ctrl:1
	v_mov_b32_dpp v34, v34 row_ror:8 row_mask:0xf bank_mask:0xf bound_ctrl:1
	v_mov_b32_dpp v42, v36 row_ror:8 row_mask:0xf bank_mask:0xf bound_ctrl:1
	v_cndmask_b32_e64 v36, v32, v44, s[0:1]
	v_cndmask_b32_e64 v32, v37, v32, s[0:1]
	v_cndmask_b32_e64 v37, v33, v45, s[0:1]
	v_cndmask_b32_e64 v33, v38, v33, s[0:1]
	v_cndmask_b32_e64 v38, v34, v40, s[0:1]
	v_cndmask_b32_e64 v34, v39, v34, s[0:1]
	v_cndmask_b32_e64 v39, v42, v41, s[0:1]
	v_cndmask_b32_e64 v35, v35, v42, s[0:1]
	v_add_u32_e32 v42, 0x90, v142
	v_add_u32_e32 v40, 0x98, v142
	s_and_b64 vcc, exec, s[6:7]
	s_mov_b64 s[28:29], -1
	s_cbranch_vccnz .LBB0_216
	v_and_b32_e32 v41, 0x1fd7, v42
	v_lshlrev_b32_e32 v44, s21, v41
	v_and_b32_e32 v44, 0x1ffe, v44
	v_lshrrev_b32_e32 v41, s17, v41
	v_lshlrev_b32_e32 v45, s21, v40
	v_and_b32_e32 v43, 0x1fdf, v40
	v_and_b32_e32 v46, 0x1ffe, v45
	v_add_lshl_u32 v44, v44, v41, 7
	v_mov_b32_e32 v45, v133
	v_lshrrev_b32_e32 v43, s17, v43
	v_lshl_add_u64 v[44:45], v[64:65], 0, v[44:45]
	global_store_dwordx4 v[44:45], v[36:39], off nt
	v_add_lshl_u32 v44, v46, v43, 7
	v_mov_b32_e32 v45, v133
	v_lshl_add_u64 v[44:45], v[64:65], 0, v[44:45]
	global_store_dwordx4 v[44:45], v[32:35], off nt
	s_cbranch_execz .LBB0_217

; __device__ __forceinline__ unsigned pk2(float lo, float hi) { f32x2_t v = {lo, hi}; bf16x2_t b = __builtin_convertvector(v, bf16x2_t); return __builtin_bit_cast(unsigned, b); }
; __device__ __forceinline__ float silu_f(float v) { return v * __builtin_amdgcn_rcpf(1.f + __builtin_amdgcn_exp2f(-v * LOG2E)); }
; template <int CTRL> __device__ __forceinline__ unsigned dpp_mov(unsigned v) { return (unsigned)__builtin_amdgcn_update_dpp(0, (int)v, CTRL, 0xF, 0xF, true); }
;     __device__ __forceinline__ void operator()(const pg8::f32x4 (&acc)[2][2][4][2], const pg8::Unit& u, int wr, int wc, int fr, int fq) const {
;     ...
;                 pg8::f32x4 a0 = acc[ai][0][m][0], a1 = acc[ai][0][m][1], b0 = acc[ai][1][m][0], b1 = acc[ai][1][m][1];
;                 if (act) {
; #pragma unroll
;                     for (int e = 0; e < 4; ++e) { a0[e] = silu_f(a0[e]); a1[e] = silu_f(a1[e]); b0[e] = silu_f(b0[e]); b1[e] = silu_f(b1[e]); } }
;                 u32x4 A, B; A.x = pk2(a0[0], a0[1]); A.y = pk2(a0[2], a0[3]); A.z = pk2(a1[0], a1[1]); A.w = pk2(a1[2], a1[3]);
;                 B.x = pk2(b0[0], b0[1]); B.y = pk2(b0[2], b0[3]); B.z = pk2(b1[0], b1[1]); B.w = pk2(b1[2], b1[3]);
;                 u32x4 snd, rcv;
; #pragma unroll
;                 for (int e = 0; e < 4; ++e) { snd[e] = hi8 ? A[e] : B[e]; rcv[e] = dpp_mov<0x128>(snd[e]); }
;                 u32x4 d1, d2;
; #pragma unroll
;                 for (int e = 0; e < 4; ++e) { d1[e] = hi8 ? rcv[e] : A[e]; d2[e] = hi8 ? B[e] : rcv[e]; }
;                 const int row1 = rbase + ai * 128 + m * 16, row2 = row1 + 8;
;                 if (qkv) {
;                     const int bb = row1 >> 13, t1 = row1 & (SEQ - 1), t2 = row2 & (SEQ - 1);
;                     const int p1 = (t1 & dmask) * Lc + (t1 >> dsh), p2 = (t2 & dmask) * Lc + (t2 >> dsh);
;                     bf16_t* hb = base + (size_t)bb * 24 * SEQ * 64 + ecol;
;                     *(u32x4*)(hb + (size_t)p1 * 64) = d1; *(u32x4*)(hb + (size_t)p2 * 64) = d2;
.Lp1_nn6:
	v_cvt_pk_bf16_f32 v28, v28, v29
	v_cvt_pk_bf16_f32 v29, v30, v31
	v_cvt_pk_bf16_f32 v24, v24, v25
	v_cvt_pk_bf16_f32 v25, v26, v27
	v_cvt_pk_bf16_f32 v21, v20, v21
	v_cvt_pk_bf16_f32 v22, v22, v23
	v_cvt_pk_bf16_f32 v23, v16, v17
	v_cvt_pk_bf16_f32 v19, v18, v19
	v_cndmask_b32_e64 v16, v28, v21, s[0:1]
	v_cndmask_b32_e64 v17, v29, v22, s[0:1]
	v_cndmask_b32_e64 v18, v24, v23, s[0:1]
	v_cndmask_b32_e64 v20, v25, v19, s[0:1]
	v_mov_b32_dpp v16, v16 row_ror:8 row_mask:0xf bank_mask:0xf bound_ctrl:1
	v_mov_b32_dpp v17, v17 row_ror:8 row_mask:0xf bank_mask:0xf bound_ctrl:1
	v_mov_b32_dpp v18, v18 row_ror:8 row_mask:0xf bank_mask:0xf bound_ctrl:1
	v_mov_b32_dpp v26, v20 row_ror:8 row_mask:0xf bank_mask:0xf bound_ctrl:1
	v_cndmask_b32_e64 v20, v16, v28, s[0:1]
	v_cndmask_b32_e64 v16, v21, v16, s[0:1]
	v_cndmask_b32_e64 v21, v17, v29, s[0:1]
	v_cndmask_b32_e64 v17, v22, v17, s[0:1]
	v_cndmask_b32_e64 v22, v18, v24, s[0:1]
	v_cndmask_b32_e64 v18, v23, v18, s[0:1]
	v_cndmask_b32_e64 v23, v26, v25, s[0:1]
	v_cndmask_b32_e64 v19, v19, v26, s[0:1]
	v_add_u32_e32 v26, 0xa0, v142
	v_add_u32_e32 v24, 0xa8, v142
	s_and_b64 vcc, exec, s[6:7]
	s_mov_b64 s[28:29], -1
	s_cbranch_vccnz .LBB0_218
	v_and_b32_e32 v25, 0x1fe7, v26
	v_lshlrev_b32_e32 v28, s21, v25
	v_and_b32_e32 v28, 0x1ffe, v28
	v_lshrrev_b32_e32 v25, s17, v25
	v_lshlrev_b32_e32 v29, s21, v24
	v_and_b32_e32 v27, 0x1fef, v24
	v_and_b32_e32 v30, 0x1ffe, v29
	v_add_lshl_u32 v28, v28, v25, 7
	v_mov_b32_e32 v29, v133
	v_lshrrev_b32_e32 v27, s17, v27
	v_lshl_add_u64 v[28:29], v[64:65], 0, v[28:29]
	global_store_dwordx4 v[28:29], v[20:23], off nt
	v_add_lshl_u32 v28, v30, v27, 7
	v_mov_b32_e32 v29, v133
	v_lshl_add_u64 v[28:29], v[64:65], 0, v[28:29]
	global_store_dwordx4 v[28:29], v[16:19], off nt
	s_cbranch_execz .LBB0_219

; __device__ __forceinline__ unsigned pk2(float lo, float hi) { f32x2_t v = {lo, hi}; bf16x2_t b = __builtin_convertvector(v, bf16x2_t); return __builtin_bit_cast(unsigned, b); }
; __device__ __forceinline__ float silu_f(float v) { return v * __builtin_amdgcn_rcpf(1.f + __builtin_amdgcn_exp2f(-v * LOG2E)); }
; template <int CTRL> __device__ __forceinline__ unsigned dpp_mov(unsigned v) { return (unsigned)__builtin_amdgcn_update_dpp(0, (int)v, CTRL, 0xF, 0xF, true); }
;     __device__ __forceinline__ void operator()(const pg8::f32x4 (&acc)[2][2][4][2], const pg8::Unit& u, int wr, int wc, int fr, int fq) const {
;     ...
;                 pg8::f32x4 a0 = acc[ai][0][m][0], a1 = acc[ai][0][m][1], b0 = acc[ai][1][m][0], b1 = acc[ai][1][m][1];
;                 if (act) {
; #pragma unroll
;                     for (int e = 0; e < 4; ++e) { a0[e] = silu_f(a0[e]); a1[e] = silu_f(a1[e]); b0[e] = silu_f(b0[e]); b1[e] = silu_f(b1[e]); } }
;                 u32x4 A, B; A.x = pk2(a0[0], a0[1]); A.y = pk2(a0[2], a0[3]); A.z = pk2(a1[0], a1[1]); A.w = pk2(a1[2], a1[3]);
;                 B.x = pk2(b0[0], b0[1]); B.y = pk2(b0[2], b0[3]); B.z = pk2(b1[0], b1[1]); B.w = pk2(b1[2], b1[3]);
;                 u32x4 snd, rcv;
; #pragma unroll
;                 for (int e = 0; e < 4; ++e) { snd[e] = hi8 ? A[e] : B[e]; rcv[e] = dpp_mov<0x128>(snd[e]); }
;                 u32x4 d1, d2;
; #pragma unroll
;                 for (int e = 0; e < 4; ++e) { d1[e] = hi8 ? rcv[e] : A[e]; d2[e] = hi8 ? B[e] : rcv[e]; }
;                 const int row1 = rbase + ai * 128 + m * 16, row2 = row1 + 8;
;                 if (qkv) {
;                     const int bb = row1 >> 13, t1 = row1 & (SEQ - 1), t2 = row2 & (SEQ - 1);
;                     const int p1 = (t1 & dmask) * Lc + (t1 >> dsh), p2 = (t2 & dmask) * Lc + (t2 >> dsh);
;                     bf16_t* hb = base + (size_t)bb * 24 * SEQ * 64 + ecol;
;                     *(u32x4*)(hb + (size_t)p1 * 64) = d1; *(u32x4*)(hb + (size_t)p2 * 64) = d2;
.Lp1_nn7:
	v_cvt_pk_bf16_f32 v12, v12, v13
	v_cvt_pk_bf16_f32 v13, v14, v15
	v_cvt_pk_bf16_f32 v8, v8, v9
	v_cvt_pk_bf16_f32 v9, v10, v11
	v_cvt_pk_bf16_f32 v5, v4, v5
	v_cvt_pk_bf16_f32 v6, v6, v7
	v_cvt_pk_bf16_f32 v7, v0, v1
	v_cvt_pk_bf16_f32 v3, v2, v3
	v_cndmask_b32_e64 v0, v12, v5, s[0:1]
	v_cndmask_b32_e64 v1, v13, v6, s[0:1]
	v_cndmask_b32_e64 v2, v8, v7, s[0:1]
	v_cndmask_b32_e64 v4, v9, v3, s[0:1]
	v_mov_b32_dpp v0, v0 row_ror:8 row_mask:0xf bank_mask:0xf bound_ctrl:1
	v_mov_b32_dpp v1, v1 row_ror:8 row_mask:0xf bank_mask:0xf bound_ctrl:1
	v_mov_b32_dpp v2, v2 row_ror:8 row_mask:0xf bank_mask:0xf bound_ctrl:1
	v_mov_b32_dpp v10, v4 row_ror:8 row_mask:0xf bank_mask:0xf bound_ctrl:1
	v_cndmask_b32_e64 v4, v0, v12, s[0:1]
	v_cndmask_b32_e64 v0, v5, v0, s[0:1]
	v_cndmask_b32_e64 v5, v1, v13, s[0:1]
	v_cndmask_b32_e64 v1, v6, v1, s[0:1]
	v_cndmask_b32_e64 v6, v2, v8, s[0:1]
	v_cndmask_b32_e64 v2, v7, v2, s[0:1]
	v_cndmask_b32_e64 v7, v10, v9, s[0:1]
	v_cndmask_b32_e64 v3, v3, v10, s[0:1]
	v_add_u32_e32 v10, 0xb0, v142
	v_add_u32_e32 v8, 0xb8, v142
	s_and_b64 vcc, exec, s[6:7]
	s_mov_b64 s[4:5], -1
	s_cbranch_vccnz .LBB0_220
	v_and_b32_e32 v9, 0x1ff7, v10
	v_lshlrev_b32_e32 v12, s21, v9
	v_and_b32_e32 v12, 0x1ffe, v12
	v_lshrrev_b32_e32 v9, s17, v9
	v_lshlrev_b32_e32 v13, s21, v8
	v_and_b32_e32 v11, 0x1fff, v8
	v_and_b32_e32 v14, 0x1ffe, v13
	v_add_lshl_u32 v12, v12, v9, 7
	v_mov_b32_e32 v13, v133
	v_lshrrev_b32_e32 v11, s17, v11
	v_lshl_add_u64 v[12:13], v[64:65], 0, v[12:13]
	global_store_dwordx4 v[12:13], v[4:7], off nt
	v_add_lshl_u32 v12, v14, v11, 7
	v_mov_b32_e32 v13, v133
	v_lshl_add_u64 v[12:13], v[64:65], 0, v[12:13]
	global_store_dwordx4 v[12:13], v[0:3], off nt
	s_cbranch_execz .LBB0_221

;     __device__ __forceinline__ void operator()(const pg8::f32x4 (&acc)[2][2][4][2], const pg8::Unit& u, int wr, int wc, int fr, int fq) const {
;     ...
;                 const int row1 = rbase + ai * 128 + m * 16, row2 = row1 + 8;
;                 if (qkv) {
;                     const int bb = row1 >> 13, t1 = row1 & (SEQ - 1), t2 = row2 & (SEQ - 1);
;                     const int p1 = (t1 & dmask) * Lc + (t1 >> dsh), p2 = (t2 & dmask) * Lc + (t2 >> dsh);
;                     bf16_t* hb = base + (size_t)bb * 24 * SEQ * 64 + ecol;
;                     *(u32x4*)(hb + (size_t)p1 * 64) = d1; *(u32x4*)(hb + (size_t)p2 * 64) = d2;
;                 } else {
;                     *(u32x4*)(base + (size_t)row1 * ld + ecol) = d1; *(u32x4*)(base + (size_t)row2 * ld + ecol) = d2;
.LBB0_207:
	v_ashrrev_i32_e32 v143, 31, v142
	v_lshlrev_b64 v[122:123], s8, v[142:143]
	v_lshl_add_u64 v[122:123], v[122:123], 1, v[140:141]
	v_ashrrev_i32_e32 v121, 31, v120
	global_store_dwordx4 v[122:123], v[116:119], off nt
	s_nop 1
	v_lshlrev_b64 v[116:117], s8, v[120:121]
	v_lshl_add_u64 v[116:117], v[116:117], 1, v[140:141]
	global_store_dwordx4 v[116:117], v[112:115], off nt
	s_and_b64 vcc, exec, s[4:5]
	s_cbranch_vccz .LBB0_178
	s_branch .LBB0_179

;     __device__ __forceinline__ void operator()(const pg8::f32x4 (&acc)[2][2][4][2], const pg8::Unit& u, int wr, int wc, int fr, int fq) const {
;     ...
;                 const int row1 = rbase + ai * 128 + m * 16, row2 = row1 + 8;
;                 if (qkv) {
;                     const int bb = row1 >> 13, t1 = row1 & (SEQ - 1), t2 = row2 & (SEQ - 1);
;                     const int p1 = (t1 & dmask) * Lc + (t1 >> dsh), p2 = (t2 & dmask) * Lc + (t2 >> dsh);
;                     bf16_t* hb = base + (size_t)bb * 24 * SEQ * 64 + ecol;
;                     *(u32x4*)(hb + (size_t)p1 * 64) = d1; *(u32x4*)(hb + (size_t)p2 * 64) = d2;
;                 } else {
;                     *(u32x4*)(base + (size_t)row1 * ld + ecol) = d1; *(u32x4*)(base + (size_t)row2 * ld + ecol) = d2;
.LBB0_209:
	v_ashrrev_i32_e32 v107, 31, v106
	v_lshlrev_b64 v[106:107], s8, v[106:107]
	v_lshl_add_u64 v[106:107], v[106:107], 1, v[140:141]
	v_ashrrev_i32_e32 v105, 31, v104
	global_store_dwordx4 v[106:107], v[100:103], off nt
	s_nop 1
	v_lshlrev_b64 v[100:101], s8, v[104:105]
	v_lshl_add_u64 v[100:101], v[100:101], 1, v[140:141]
	global_store_dwordx4 v[100:101], v[96:99], off nt
	s_and_b64 vcc, exec, s[4:5]
	s_cbranch_vccz .LBB0_182
	s_branch .LBB0_183

;     __device__ __forceinline__ void operator()(const pg8::f32x4 (&acc)[2][2][4][2], const pg8::Unit& u, int wr, int wc, int fr, int fq) const {
;     ...
;                 const int row1 = rbase + ai * 128 + m * 16, row2 = row1 + 8;
;                 if (qkv) {
;                     const int bb = row1 >> 13, t1 = row1 & (SEQ - 1), t2 = row2 & (SEQ - 1);
;                     const int p1 = (t1 & dmask) * Lc + (t1 >> dsh), p2 = (t2 & dmask) * Lc + (t2 >> dsh);
;                     bf16_t* hb = base + (size_t)bb * 24 * SEQ * 64 + ecol;
;                     *(u32x4*)(hb + (size_t)p1 * 64) = d1; *(u32x4*)(hb + (size_t)p2 * 64) = d2;
;                 } else {
;                     *(u32x4*)(base + (size_t)row1 * ld + ecol) = d1; *(u32x4*)(base + (size_t)row2 * ld + ecol) = d2;
.LBB0_211:
	v_ashrrev_i32_e32 v91, 31, v90
	v_lshlrev_b64 v[90:91], s8, v[90:91]
	v_lshl_add_u64 v[90:91], v[90:91], 1, v[140:141]
	v_ashrrev_i32_e32 v89, 31, v88
	global_store_dwordx4 v[90:91], v[84:87], off nt
	s_nop 1
	v_lshlrev_b64 v[84:85], s8, v[88:89]
	v_lshl_add_u64 v[84:85], v[84:85], 1, v[140:141]
	global_store_dwordx4 v[84:85], v[80:83], off nt
	s_and_b64 vcc, exec, s[4:5]
	s_cbranch_vccz .LBB0_186
	s_branch .LBB0_187

;     __device__ __forceinline__ void operator()(const pg8::f32x4 (&acc)[2][2][4][2], const pg8::Unit& u, int wr, int wc, int fr, int fq) const {
;     ...
;                 const int row1 = rbase + ai * 128 + m * 16, row2 = row1 + 8;
;                 if (qkv) {
;                     const int bb = row1 >> 13, t1 = row1 & (SEQ - 1), t2 = row2 & (SEQ - 1);
;                     const int p1 = (t1 & dmask) * Lc + (t1 >> dsh), p2 = (t2 & dmask) * Lc + (t2 >> dsh);
;                     bf16_t* hb = base + (size_t)bb * 24 * SEQ * 64 + ecol;
;                     *(u32x4*)(hb + (size_t)p1 * 64) = d1; *(u32x4*)(hb + (size_t)p2 * 64) = d2;
;                 } else {
;                     *(u32x4*)(base + (size_t)row1 * ld + ecol) = d1; *(u32x4*)(base + (size_t)row2 * ld + ecol) = d2;
.LBB0_213:
	v_ashrrev_i32_e32 v75, 31, v74
	v_lshlrev_b64 v[74:75], s8, v[74:75]
	v_lshl_add_u64 v[74:75], v[74:75], 1, v[140:141]
	v_ashrrev_i32_e32 v73, 31, v72
	global_store_dwordx4 v[74:75], v[68:71], off nt
	s_nop 1
	v_lshlrev_b64 v[68:69], s8, v[72:73]
	v_lshl_add_u64 v[68:69], v[68:69], 1, v[140:141]
	global_store_dwordx4 v[68:69], v[64:67], off nt
	s_and_b64 vcc, exec, s[4:5]
	s_cbranch_vccz .LBB0_190
	s_branch .LBB0_191

;     __device__ __forceinline__ void operator()(const pg8::f32x4 (&acc)[2][2][4][2], const pg8::Unit& u, int wr, int wc, int fr, int fq) const {
;     ...
;                 const int row1 = rbase + ai * 128 + m * 16, row2 = row1 + 8;
;                 if (qkv) {
;                     const int bb = row1 >> 13, t1 = row1 & (SEQ - 1), t2 = row2 & (SEQ - 1);
;                     const int p1 = (t1 & dmask) * Lc + (t1 >> dsh), p2 = (t2 & dmask) * Lc + (t2 >> dsh);
;                     bf16_t* hb = base + (size_t)bb * 24 * SEQ * 64 + ecol;
;                     *(u32x4*)(hb + (size_t)p1 * 64) = d1; *(u32x4*)(hb + (size_t)p2 * 64) = d2;
;                 } else {
;                     *(u32x4*)(base + (size_t)row1 * ld + ecol) = d1; *(u32x4*)(base + (size_t)row2 * ld + ecol) = d2;
.LBB0_215:
	v_ashrrev_i32_e32 v67, 31, v66
	v_lshlrev_b64 v[58:59], s8, v[66:67]
	v_lshl_add_u64 v[58:59], v[58:59], 1, v[140:141]
	v_ashrrev_i32_e32 v57, 31, v56
	global_store_dwordx4 v[58:59], v[52:55], off nt
	s_nop 1
	v_lshlrev_b64 v[52:53], s8, v[56:57]
	v_lshl_add_u64 v[52:53], v[52:53], 1, v[140:141]
	global_store_dwordx4 v[52:53], v[48:51], off nt
	s_and_b64 vcc, exec, s[4:5]
	s_cbranch_vccz .LBB0_194
	s_branch .LBB0_195

;     __device__ __forceinline__ void operator()(const pg8::f32x4 (&acc)[2][2][4][2], const pg8::Unit& u, int wr, int wc, int fr, int fq) const {
;     ...
;                 const int row1 = rbase + ai * 128 + m * 16, row2 = row1 + 8;
;                 if (qkv) {
;                     const int bb = row1 >> 13, t1 = row1 & (SEQ - 1), t2 = row2 & (SEQ - 1);
;                     const int p1 = (t1 & dmask) * Lc + (t1 >> dsh), p2 = (t2 & dmask) * Lc + (t2 >> dsh);
;                     bf16_t* hb = base + (size_t)bb * 24 * SEQ * 64 + ecol;
;                     *(u32x4*)(hb + (size_t)p1 * 64) = d1; *(u32x4*)(hb + (size_t)p2 * 64) = d2;
;                 } else {
;                     *(u32x4*)(base + (size_t)row1 * ld + ecol) = d1; *(u32x4*)(base + (size_t)row2 * ld + ecol) = d2;
.LBB0_217:
	v_ashrrev_i32_e32 v43, 31, v42
	v_lshlrev_b64 v[42:43], s8, v[42:43]
	v_lshl_add_u64 v[42:43], v[42:43], 1, v[140:141]
	v_ashrrev_i32_e32 v41, 31, v40
	global_store_dwordx4 v[42:43], v[36:39], off nt
	s_nop 1
	v_lshlrev_b64 v[36:37], s8, v[40:41]
	v_lshl_add_u64 v[36:37], v[36:37], 1, v[140:141]
	global_store_dwordx4 v[36:37], v[32:35], off nt
	s_and_b64 vcc, exec, s[4:5]
	s_cbranch_vccz .LBB0_198
	s_branch .LBB0_199

;     __device__ __forceinline__ void operator()(const pg8::f32x4 (&acc)[2][2][4][2], const pg8::Unit& u, int wr, int wc, int fr, int fq) const {
;     ...
;                 const int row1 = rbase + ai * 128 + m * 16, row2 = row1 + 8;
;                 if (qkv) {
;                     const int bb = row1 >> 13, t1 = row1 & (SEQ - 1), t2 = row2 & (SEQ - 1);
;                     const int p1 = (t1 & dmask) * Lc + (t1 >> dsh), p2 = (t2 & dmask) * Lc + (t2 >> dsh);
;                     bf16_t* hb = base + (size_t)bb * 24 * SEQ * 64 + ecol;
;                     *(u32x4*)(hb + (size_t)p1 * 64) = d1; *(u32x4*)(hb + (size_t)p2 * 64) = d2;
;                 } else {
;                     *(u32x4*)(base + (size_t)row1 * ld + ecol) = d1; *(u32x4*)(base + (size_t)row2 * ld + ecol) = d2;
.LBB0_219:
	v_ashrrev_i32_e32 v27, 31, v26
	v_lshlrev_b64 v[26:27], s8, v[26:27]
	v_lshl_add_u64 v[26:27], v[26:27], 1, v[140:141]
	v_ashrrev_i32_e32 v25, 31, v24
	global_store_dwordx4 v[26:27], v[20:23], off nt
	s_nop 1
	v_lshlrev_b64 v[20:21], s8, v[24:25]
	v_lshl_add_u64 v[20:21], v[20:21], 1, v[140:141]
	global_store_dwordx4 v[20:21], v[16:19], off nt
	s_and_b64 vcc, exec, s[4:5]
	s_cbranch_vccz .LBB0_202
	s_branch .LBB0_203

;     __device__ __forceinline__ void operator()(const pg8::f32x4 (&acc)[2][2][4][2], const pg8::Unit& u, int wr, int wc, int fr, int fq) const {
;     ...
;                 const int row1 = rbase + ai * 128 + m * 16, row2 = row1 + 8;
;                 if (qkv) {
;                     const int bb = row1 >> 13, t1 = row1 & (SEQ - 1), t2 = row2 & (SEQ - 1);
;                     const int p1 = (t1 & dmask) * Lc + (t1 >> dsh), p2 = (t2 & dmask) * Lc + (t2 >> dsh);
;                     bf16_t* hb = base + (size_t)bb * 24 * SEQ * 64 + ecol;
;                     *(u32x4*)(hb + (size_t)p1 * 64) = d1; *(u32x4*)(hb + (size_t)p2 * 64) = d2;
;                 } else {
;                     *(u32x4*)(base + (size_t)row1 * ld + ecol) = d1; *(u32x4*)(base + (size_t)row2 * ld + ecol) = d2;
.LBB0_221:
	v_ashrrev_i32_e32 v11, 31, v10
	v_lshlrev_b64 v[10:11], s8, v[10:11]
	v_lshl_add_u64 v[10:11], v[10:11], 1, v[140:141]
	v_ashrrev_i32_e32 v9, 31, v8
	global_store_dwordx4 v[10:11], v[4:7], off nt
	s_nop 1
	v_lshlrev_b64 v[4:5], s8, v[8:9]
	v_lshl_add_u64 v[4:5], v[4:5], 1, v[140:141]
	global_store_dwordx4 v[4:5], v[0:3], off nt
	s_andn2_b64 vcc, exec, s[22:23]
	s_mov_b64 s[4:5], -1
	s_cbranch_vccnz .LBB0_153
